# baseline (speedup 1.0000x reference)
.LBB0_395:
.Lfz1_c0:
	s_branch .Ldummy_0

.LBB0_413:
	v_add_u32_e32 v242, s27, v234
	ds_read_b64_tr_b16 v[160:161], v242 offset:0x0
	ds_read_b64_tr_b16 v[162:163], v242 offset:0x100
	ds_read_b64_tr_b16 v[164:165], v242 offset:0x1000
	ds_read_b64_tr_b16 v[166:167], v242 offset:0x1100
	s_waitcnt lgkmcnt(2)
	v_mfma_f32_32x32x16_bf16 v[128:143], v[216:219], v[160:163], v[128:143]
	ds_read_b64_tr_b16 v[168:169], v242 offset:0x200
	v_mfma_f32_32x32x16_bf16 v[96:111], v[212:215], v[160:163], v[96:111]
	ds_read_b64_tr_b16 v[170:171], v242 offset:0x300
	s_waitcnt lgkmcnt(2)
	v_mfma_f32_32x32x16_bf16 v[128:143], v[224:227], v[164:167], v[128:143]
	ds_read_b64_tr_b16 v[172:173], v242 offset:0x1200
	v_mfma_f32_32x32x16_bf16 v[96:111], v[220:223], v[164:167], v[96:111]
	ds_read_b64_tr_b16 v[174:175], v242 offset:0x1300
	s_waitcnt lgkmcnt(2)
	v_mfma_f32_32x32x16_bf16 v[112:127], v[216:219], v[168:171], v[112:127]
	ds_read_b64_tr_b16 v[160:161], v242 offset:0x400
	v_mfma_f32_32x32x16_bf16 v[80:95], v[212:215], v[168:171], v[80:95]
	ds_read_b64_tr_b16 v[162:163], v242 offset:0x500
	s_waitcnt lgkmcnt(2)
	v_mfma_f32_32x32x16_bf16 v[112:127], v[224:227], v[172:175], v[112:127]
	ds_read_b64_tr_b16 v[164:165], v242 offset:0x1400
	v_mfma_f32_32x32x16_bf16 v[80:95], v[220:223], v[172:175], v[80:95]
	ds_read_b64_tr_b16 v[166:167], v242 offset:0x1500
	ds_read_b128 v[144:147], v241 offset:0x2000
	ds_read_b128 v[148:151], v240 offset:0x2000
	ds_read_b128 v[152:155], v239 offset:0x2000
	ds_read_b128 v[156:159], v0 offset:0x2000
	s_waitcnt lgkmcnt(6)
	v_mfma_f32_32x32x16_bf16 v[64:79], v[216:219], v[160:163], v[64:79]
	ds_read_b64_tr_b16 v[168:169], v242 offset:0x600
	v_mfma_f32_32x32x16_bf16 v[32:47], v[212:215], v[160:163], v[32:47]
	ds_read_b64_tr_b16 v[170:171], v242 offset:0x700
	s_waitcnt lgkmcnt(6)
	v_mfma_f32_32x32x16_bf16 v[64:79], v[224:227], v[164:167], v[64:79]
	ds_read_b64_tr_b16 v[172:173], v242 offset:0x1600
	v_mfma_f32_32x32x16_bf16 v[32:47], v[220:223], v[164:167], v[32:47]
	ds_read_b64_tr_b16 v[174:175], v242 offset:0x1700
	s_waitcnt lgkmcnt(2)
	v_mfma_f32_32x32x16_bf16 v[48:63], v[216:219], v[168:171], v[48:63]
	v_mfma_f32_32x32x16_bf16 v[16:31], v[212:215], v[168:171], v[16:31]
	s_waitcnt lgkmcnt(0)
	v_mfma_f32_32x32x16_bf16 v[48:63], v[224:227], v[172:175], v[48:63]
	v_mfma_f32_32x32x16_bf16 v[16:31], v[220:223], v[172:175], v[16:31]
	s_waitcnt lgkmcnt(0)
	s_branch .Ldummy_1
.Ldummy_1:
	v_mfma_f32_32x32x16_bf16 v[212:227], v[144:147], v[176:179], 0
	v_mfma_f32_32x32x16_bf16 v[212:227], v[148:151], v[180:183], v[212:227]
	v_mfma_f32_32x32x16_bf16 v[212:227], v[152:155], v[184:187], v[212:227]
	v_mfma_f32_32x32x16_bf16 v[212:227], v[156:159], v[188:191], v[212:227]
	ds_read_b128 v[144:147], v241 offset:0x2080
	ds_read_b128 v[148:151], v240 offset:0x2080
	ds_read_b128 v[152:155], v239 offset:0x2080
	ds_read_b128 v[156:159], v0 offset:0x2080
	v_cmp_eq_f32_e32 vcc, 0, v238
	v_cmp_eq_f32_e64 s[10:11], 0, v237
	s_and_b64 s[0:1], vcc, s[10:11]
	s_cmp_eq_u64 s[0:1], exec
	s_waitcnt lgkmcnt(0)
	v_mfma_f32_32x32x16_bf16 v[160:175], v[144:147], v[192:195], 0
	v_mfma_f32_32x32x16_bf16 v[160:175], v[148:151], v[196:199], v[160:175]
	v_mfma_f32_32x32x16_bf16 v[160:175], v[152:155], v[200:203], v[160:175]
	v_mfma_f32_32x32x16_bf16 v[160:175], v[156:159], v[204:207], v[160:175]
	s_cbranch_scc0 .Lfz2o_c0
	v_exp_f32_e32 v144, v212
	v_exp_f32_e32 v145, v213
	v_exp_f32_e32 v146, v214
	v_exp_f32_e32 v147, v215
	v_exp_f32_e32 v148, v216
	v_exp_f32_e32 v149, v217
	v_exp_f32_e32 v150, v218
	v_exp_f32_e32 v151, v219
	v_exp_f32_e32 v152, v220
	v_exp_f32_e32 v153, v221
	v_exp_f32_e32 v154, v222
	v_exp_f32_e32 v155, v223
	v_exp_f32_e32 v156, v224
	v_exp_f32_e32 v157, v225
	v_exp_f32_e32 v158, v226
	v_exp_f32_e32 v159, v227
	v_add_f32_e32 v252, v144, v145
	v_add_f32_e32 v253, v146, v147
	v_add_f32_e32 v254, v148, v149
	v_add_f32_e32 v255, v150, v151
	v_add_f32_e32 v252, v252, v152
	v_add_f32_e32 v253, v253, v153
	v_add_f32_e32 v254, v254, v154
	v_add_f32_e32 v255, v255, v155
	v_add_f32_e32 v252, v252, v156
	v_add_f32_e32 v253, v253, v157
	v_add_f32_e32 v254, v254, v158
	v_add_f32_e32 v255, v255, v159
	v_cvt_pk_bf16_f32 v6, v144, v145
	v_cvt_pk_bf16_f32 v7, v146, v147
	v_add_f32_e32 v252, v252, v253
	v_add_f32_e32 v254, v254, v255
	v_cvt_pk_bf16_f32 v8, v148, v149
	v_cvt_pk_bf16_f32 v9, v150, v151
	v_cvt_pk_bf16_f32 v208, v152, v153
	v_add_f32_e32 v252, v252, v254
	v_cvt_pk_bf16_f32 v209, v154, v155
	v_cvt_pk_bf16_f32 v210, v156, v157
	v_cvt_pk_bf16_f32 v211, v158, v159
	v_add_u32_e32 v253, 0xde801b54, v252
	v_cmp_gt_u32_e32 vcc, 0x3bff7543, v253
	s_cmp_lg_u64 vcc, exec
	s_cbranch_scc1 .LBB0_444
	v_add_f32_e32 v15, v15, v252
	v_exp_f32_e32 v144, v160
	v_exp_f32_e32 v145, v161
	v_exp_f32_e32 v146, v162
	v_exp_f32_e32 v147, v163
	v_exp_f32_e32 v148, v164
	v_exp_f32_e32 v149, v165
	v_exp_f32_e32 v150, v166
	v_exp_f32_e32 v151, v167
	v_exp_f32_e32 v152, v168
	v_exp_f32_e32 v153, v169
	v_exp_f32_e32 v154, v170
	v_exp_f32_e32 v155, v171
	v_exp_f32_e32 v156, v172
	v_exp_f32_e32 v157, v173
	v_exp_f32_e32 v158, v174
	v_exp_f32_e32 v159, v175
	v_add_f32_e32 v252, v144, v145
	v_add_f32_e32 v253, v146, v147
	v_add_f32_e32 v254, v148, v149
	v_add_f32_e32 v255, v150, v151
	v_add_f32_e32 v252, v252, v152
	v_add_f32_e32 v253, v253, v153
	v_add_f32_e32 v254, v254, v154
	v_add_f32_e32 v255, v255, v155
	v_add_f32_e32 v252, v252, v156
	v_add_f32_e32 v253, v253, v157
	v_add_f32_e32 v254, v254, v158
	v_add_f32_e32 v255, v255, v159
	v_cvt_pk_bf16_f32 v2, v144, v145
	v_cvt_pk_bf16_f32 v3, v146, v147
	v_add_f32_e32 v252, v252, v253
	v_add_f32_e32 v254, v254, v255
	v_cvt_pk_bf16_f32 v4, v148, v149
	v_cvt_pk_bf16_f32 v5, v150, v151
	v_cvt_pk_bf16_f32 v10, v152, v153
	v_add_f32_e32 v252, v252, v254
	v_cvt_pk_bf16_f32 v11, v154, v155
	v_cvt_pk_bf16_f32 v12, v156, v157
	v_cvt_pk_bf16_f32 v13, v158, v159
	v_add_u32_e32 v253, 0xde801b54, v252
	v_cmp_gt_u32_e32 vcc, 0x3bff7543, v253
	s_cmp_lg_u64 vcc, exec
	s_cbranch_scc1 .Lfzsb2_c0
	v_add_f32_e32 v14, v14, v252
	s_branch .LBB0_429

.LBB0_1267:
	v_add_u32_e32 v242, s27, v234
	ds_read_b64_tr_b16 v[160:161], v242 offset:0x0
	ds_read_b64_tr_b16 v[162:163], v242 offset:0x100
	ds_read_b64_tr_b16 v[164:165], v242 offset:0x1000
	ds_read_b64_tr_b16 v[166:167], v242 offset:0x1100
	s_waitcnt lgkmcnt(2)
	v_mfma_f32_32x32x16_bf16 v[128:143], v[216:219], v[160:163], v[128:143]
	ds_read_b64_tr_b16 v[168:169], v242 offset:0x200
	v_mfma_f32_32x32x16_bf16 v[96:111], v[212:215], v[160:163], v[96:111]
	ds_read_b64_tr_b16 v[170:171], v242 offset:0x300
	s_waitcnt lgkmcnt(2)
	v_mfma_f32_32x32x16_bf16 v[128:143], v[224:227], v[164:167], v[128:143]
	ds_read_b64_tr_b16 v[172:173], v242 offset:0x1200
	v_mfma_f32_32x32x16_bf16 v[96:111], v[220:223], v[164:167], v[96:111]
	ds_read_b64_tr_b16 v[174:175], v242 offset:0x1300
	s_waitcnt lgkmcnt(2)
	v_mfma_f32_32x32x16_bf16 v[112:127], v[216:219], v[168:171], v[112:127]
	ds_read_b64_tr_b16 v[160:161], v242 offset:0x400
	v_mfma_f32_32x32x16_bf16 v[80:95], v[212:215], v[168:171], v[80:95]
	ds_read_b64_tr_b16 v[162:163], v242 offset:0x500
	s_waitcnt lgkmcnt(2)
	v_mfma_f32_32x32x16_bf16 v[112:127], v[224:227], v[172:175], v[112:127]
	ds_read_b64_tr_b16 v[164:165], v242 offset:0x1400
	v_mfma_f32_32x32x16_bf16 v[80:95], v[220:223], v[172:175], v[80:95]
	ds_read_b64_tr_b16 v[166:167], v242 offset:0x1500
	ds_read_b128 v[144:147], v241 offset:0x2000
	ds_read_b128 v[148:151], v240 offset:0x2000
	ds_read_b128 v[152:155], v239 offset:0x2000
	ds_read_b128 v[156:159], v0 offset:0x2000
	s_waitcnt lgkmcnt(6)
	v_mfma_f32_32x32x16_bf16 v[64:79], v[216:219], v[160:163], v[64:79]
	ds_read_b64_tr_b16 v[168:169], v242 offset:0x600
	v_mfma_f32_32x32x16_bf16 v[48:63], v[212:215], v[160:163], v[48:63]
	ds_read_b64_tr_b16 v[170:171], v242 offset:0x700
	s_waitcnt lgkmcnt(6)
	v_mfma_f32_32x32x16_bf16 v[64:79], v[224:227], v[164:167], v[64:79]
	ds_read_b64_tr_b16 v[172:173], v242 offset:0x1600
	v_mfma_f32_32x32x16_bf16 v[48:63], v[220:223], v[164:167], v[48:63]
	ds_read_b64_tr_b16 v[174:175], v242 offset:0x1700
	s_waitcnt lgkmcnt(2)
	v_mfma_f32_32x32x16_bf16 v[32:47], v[216:219], v[168:171], v[32:47]
	v_mfma_f32_32x32x16_bf16 v[16:31], v[212:215], v[168:171], v[16:31]
	s_waitcnt lgkmcnt(0)
	v_mfma_f32_32x32x16_bf16 v[32:47], v[224:227], v[172:175], v[32:47]
	v_mfma_f32_32x32x16_bf16 v[16:31], v[220:223], v[172:175], v[16:31]
	s_waitcnt lgkmcnt(0)
	s_branch .Ldummy_3

.LBB0_2121:
	v_add_u32_e32 v242, s27, v234
	ds_read_b64_tr_b16 v[160:161], v242 offset:0x0
	ds_read_b64_tr_b16 v[162:163], v242 offset:0x100
	ds_read_b64_tr_b16 v[164:165], v242 offset:0x1000
	ds_read_b64_tr_b16 v[166:167], v242 offset:0x1100
	s_waitcnt lgkmcnt(2)
	v_mfma_f32_32x32x16_bf16 v[128:143], v[216:219], v[160:163], v[128:143]
	ds_read_b64_tr_b16 v[168:169], v242 offset:0x200
	v_mfma_f32_32x32x16_bf16 v[96:111], v[212:215], v[160:163], v[96:111]
	ds_read_b64_tr_b16 v[170:171], v242 offset:0x300
	s_waitcnt lgkmcnt(2)
	v_mfma_f32_32x32x16_bf16 v[128:143], v[224:227], v[164:167], v[128:143]
	ds_read_b64_tr_b16 v[172:173], v242 offset:0x1200
	v_mfma_f32_32x32x16_bf16 v[96:111], v[220:223], v[164:167], v[96:111]
	ds_read_b64_tr_b16 v[174:175], v242 offset:0x1300
	s_waitcnt lgkmcnt(2)
	v_mfma_f32_32x32x16_bf16 v[112:127], v[216:219], v[168:171], v[112:127]
	ds_read_b64_tr_b16 v[160:161], v242 offset:0x400
	v_mfma_f32_32x32x16_bf16 v[80:95], v[212:215], v[168:171], v[80:95]
	ds_read_b64_tr_b16 v[162:163], v242 offset:0x500
	s_waitcnt lgkmcnt(2)
	v_mfma_f32_32x32x16_bf16 v[112:127], v[224:227], v[172:175], v[112:127]
	ds_read_b64_tr_b16 v[164:165], v242 offset:0x1400
	v_mfma_f32_32x32x16_bf16 v[80:95], v[220:223], v[172:175], v[80:95]
	ds_read_b64_tr_b16 v[166:167], v242 offset:0x1500
	ds_read_b128 v[144:147], v241 offset:0x2000
	ds_read_b128 v[148:151], v240 offset:0x2000
	ds_read_b128 v[156:159], v239 offset:0x2000
	ds_read_b128 v[244:247], v0 offset:0x2000
	s_waitcnt lgkmcnt(6)
	v_mfma_f32_32x32x16_bf16 v[64:79], v[216:219], v[160:163], v[64:79]
	ds_read_b64_tr_b16 v[168:169], v242 offset:0x600
	v_mfma_f32_32x32x16_bf16 v[32:47], v[212:215], v[160:163], v[32:47]
	ds_read_b64_tr_b16 v[170:171], v242 offset:0x700
	s_waitcnt lgkmcnt(6)
	v_mfma_f32_32x32x16_bf16 v[64:79], v[224:227], v[164:167], v[64:79]
	ds_read_b64_tr_b16 v[172:173], v242 offset:0x1600
	v_mfma_f32_32x32x16_bf16 v[32:47], v[220:223], v[164:167], v[32:47]
	ds_read_b64_tr_b16 v[174:175], v242 offset:0x1700
	s_waitcnt lgkmcnt(2)
	v_mfma_f32_32x32x16_bf16 v[48:63], v[216:219], v[168:171], v[48:63]
	v_mfma_f32_32x32x16_bf16 v[16:31], v[212:215], v[168:171], v[16:31]
	s_waitcnt lgkmcnt(0)
	v_mfma_f32_32x32x16_bf16 v[48:63], v[224:227], v[172:175], v[48:63]
	v_mfma_f32_32x32x16_bf16 v[16:31], v[220:223], v[172:175], v[16:31]
	s_waitcnt lgkmcnt(0)
	s_branch .Ldummy_5
.Ldummy_5:
	v_mfma_f32_32x32x16_bf16 v[212:227], v[144:147], v[176:179], 0
	v_mfma_f32_32x32x16_bf16 v[212:227], v[148:151], v[180:183], v[212:227]
	v_mfma_f32_32x32x16_bf16 v[212:227], v[156:159], v[184:187], v[212:227]
	v_mfma_f32_32x32x16_bf16 v[212:227], v[244:247], v[188:191], v[212:227]
	ds_read_b128 v[144:147], v241 offset:0x2080
	ds_read_b128 v[148:151], v240 offset:0x2080
	ds_read_b128 v[152:155], v239 offset:0x2080
	ds_read_b128 v[156:159], v0 offset:0x2080
	v_cmp_eq_f32_e32 vcc, 0, v238
	v_cmp_eq_f32_e64 s[6:7], 0, v237
	s_and_b64 s[0:1], vcc, s[6:7]
	s_cmp_eq_u64 s[0:1], exec
	s_waitcnt lgkmcnt(0)
	v_mfma_f32_32x32x16_bf16 v[160:175], v[144:147], v[192:195], 0
	v_mfma_f32_32x32x16_bf16 v[160:175], v[148:151], v[196:199], v[160:175]
	v_mfma_f32_32x32x16_bf16 v[160:175], v[152:155], v[200:203], v[160:175]
	v_mfma_f32_32x32x16_bf16 v[160:175], v[156:159], v[204:207], v[160:175]
	s_cbranch_scc0 .Lfz2o_c2
	v_exp_f32_e32 v144, v212
	v_exp_f32_e32 v145, v213
	v_exp_f32_e32 v146, v214
	v_exp_f32_e32 v147, v215
	v_exp_f32_e32 v148, v216
	v_exp_f32_e32 v149, v217
	v_exp_f32_e32 v150, v218
	v_exp_f32_e32 v151, v219
	v_exp_f32_e32 v152, v220
	v_exp_f32_e32 v153, v221
	v_exp_f32_e32 v154, v222
	v_exp_f32_e32 v155, v223
	v_exp_f32_e32 v156, v224
	v_exp_f32_e32 v157, v225
	v_exp_f32_e32 v158, v226
	v_exp_f32_e32 v159, v227
	v_add_f32_e32 v252, v144, v145
	v_add_f32_e32 v253, v146, v147
	v_add_f32_e32 v254, v148, v149
	v_add_f32_e32 v255, v150, v151
	v_add_f32_e32 v252, v252, v152
	v_add_f32_e32 v253, v253, v153
	v_add_f32_e32 v254, v254, v154
	v_add_f32_e32 v255, v255, v155
	v_add_f32_e32 v252, v252, v156
	v_add_f32_e32 v253, v253, v157
	v_add_f32_e32 v254, v254, v158
	v_add_f32_e32 v255, v255, v159
	v_cvt_pk_bf16_f32 v6, v144, v145
	v_cvt_pk_bf16_f32 v7, v146, v147
	v_add_f32_e32 v252, v252, v253
	v_add_f32_e32 v254, v254, v255
	v_cvt_pk_bf16_f32 v8, v148, v149
	v_cvt_pk_bf16_f32 v9, v150, v151
	v_cvt_pk_bf16_f32 v208, v152, v153
	v_add_f32_e32 v252, v252, v254
	v_cvt_pk_bf16_f32 v209, v154, v155
	v_cvt_pk_bf16_f32 v210, v156, v157
	v_cvt_pk_bf16_f32 v211, v158, v159
	v_add_u32_e32 v253, 0xde801b54, v252
	v_cmp_gt_u32_e32 vcc, 0x3bff7543, v253
	s_cmp_lg_u64 vcc, exec
	s_cbranch_scc1 .LBB0_2152
	v_add_f32_e32 v15, v15, v252
	v_exp_f32_e32 v144, v160
	v_exp_f32_e32 v145, v161
	v_exp_f32_e32 v146, v162
	v_exp_f32_e32 v147, v163
	v_exp_f32_e32 v148, v164
	v_exp_f32_e32 v149, v165
	v_exp_f32_e32 v150, v166
	v_exp_f32_e32 v151, v167
	v_exp_f32_e32 v152, v168
	v_exp_f32_e32 v153, v169
	v_exp_f32_e32 v154, v170
	v_exp_f32_e32 v155, v171
	v_exp_f32_e32 v156, v172
	v_exp_f32_e32 v157, v173
	v_exp_f32_e32 v158, v174
	v_exp_f32_e32 v159, v175
	v_add_f32_e32 v252, v144, v145
	v_add_f32_e32 v253, v146, v147
	v_add_f32_e32 v254, v148, v149
	v_add_f32_e32 v255, v150, v151
	v_add_f32_e32 v252, v252, v152
	v_add_f32_e32 v253, v253, v153
	v_add_f32_e32 v254, v254, v154
	v_add_f32_e32 v255, v255, v155
	v_add_f32_e32 v252, v252, v156
	v_add_f32_e32 v253, v253, v157
	v_add_f32_e32 v254, v254, v158
	v_add_f32_e32 v255, v255, v159
	v_cvt_pk_bf16_f32 v2, v144, v145
	v_cvt_pk_bf16_f32 v3, v146, v147
	v_add_f32_e32 v252, v252, v253
	v_add_f32_e32 v254, v254, v255
	v_cvt_pk_bf16_f32 v4, v148, v149
	v_cvt_pk_bf16_f32 v5, v150, v151
	v_cvt_pk_bf16_f32 v10, v152, v153
	v_add_f32_e32 v252, v252, v254
	v_cvt_pk_bf16_f32 v11, v154, v155
	v_cvt_pk_bf16_f32 v12, v156, v157
	v_cvt_pk_bf16_f32 v13, v158, v159
	v_add_u32_e32 v253, 0xde801b54, v252
	v_cmp_gt_u32_e32 vcc, 0x3bff7543, v253
	s_cmp_lg_u64 vcc, exec
	s_cbranch_scc1 .Lfzsb2_c2
	v_add_f32_e32 v14, v14, v252
	s_branch .LBB0_2137
